# first phase boundary uses the XCD-hierarchical barrier like the other 21 (no cooperative-groups grid sync in the device code)
# speedup vs baseline: 1.0146x; 1.0071x over previous
; #define LAS __attribute__((address_space(3)))
; DEV void xcd_barrier(unsigned* bar, unsigned x, volatile LAS unsigned* st) {
;   asm volatile("s_waitcnt vmcnt(0)" ::: "memory");
;   __syncthreads();
;   if (threadIdx.x == 0) {
;     __builtin_amdgcn_s_waitcnt(0);
;     unsigned nloc = st[0], nx = st[1];
;     if (nloc == 0u) { xcd_barrier_complete(bar, x, nloc, nx); st[0] = nloc; st[1] = nx; }
; __global__ void __launch_bounds__(512) mega_kernel(Params p, int ph_begin, int ph_end) {
;     ...
;   for (int ph = ph_begin; ph < ph_end; ++ph) {
;     run_phase(p, ph, smem);
;     if (ph + 1 < ph_end) {
;       if (ph == ph_begin) cg::this_grid().sync();
;       else xcd_barrier(bar, xcc, st);
;     }
.LBB0_546:
	s_add_i32 s16, s81, 1
	s_cmp_ge_i32 s16, s35
	s_mov_b64 s[0:1], -1
	s_cbranch_scc1 .LBB0_10
	s_waitcnt vmcnt(0)
	s_waitcnt vmcnt(0) lgkmcnt(0)
	s_barrier
	s_mov_b64 s[0:1], exec
	v_readlane_b32 s2, v242, 9
	v_readlane_b32 s3, v242, 10
	s_and_b64 s[2:3], s[0:1], s[2:3]
	s_mov_b64 exec, s[2:3]
	s_cbranch_execz .LBB0_600
	v_readlane_b32 s2, v240, 5
	s_waitcnt vmcnt(0) expcnt(0) lgkmcnt(0)
	s_nop 0
	v_mov_b32_e32 v0, s2
	ds_read_b32 v2, v0
	v_readlane_b32 s2, v240, 6
	s_waitcnt lgkmcnt(0)
	v_cmp_ne_u32_e32 vcc, 0, v2
	v_mov_b32_e32 v0, s2
	ds_read_b32 v0, v0
	s_cbranch_vccnz .LBB0_564
	s_mov_b32 s8, 1
	s_branch .LBB0_552
